# GLA scan: barrier publishing the intra-chunk matrix moved into section D in front of its first read, so waves 4-7 run their qe@S MFMAs while waves 0-3 compute the matrix
# speedup vs baseline: 1.0102x; 1.0045x over previous
; __device__ __forceinline__ int v_rd_base(int lane) { return ((lane & 3) << 3) | (((lane >> 2) & 3) << 6) | (((lane >> 4) & 1) << 5) | (((lane >> 5) & 1) << 8); }
; #define OPAQUE_TID(name) int name = MK_TID; asm volatile("" : "+v"(name))
; #define GLA_LOADV() do { vl0 = tr_read<v_rd_off(0, 0, 0)>(vb); vh0 = tr_read<v_rd_off(0, 0, 1)>(vb); vl1 = tr_read<v_rd_off(0, 1, 0)>(vb); vh1 = tr_read<v_rd_off(0, 1, 1)>(vb); \
;               vl2 = tr_read<v_rd_off(0, 2, 0)>(vb); vh2 = tr_read<v_rd_off(0, 2, 1)>(vb); vl3 = tr_read<v_rd_off(0, 3, 0)>(vb); vh3 = tr_read<v_rd_off(0, 3, 1)>(vb); } while (0)
; __device__ __forceinline__ void scan_unit(const int unit, const Args& a, unsigned char* lds, const int mk_wid) {
;     ...
;             __syncthreads();
;         }
;         { OPAQUE_TID(t_); const int lane = t_ & 63, r32 = lane & 31, hi = lane >> 5;
;           const int vb = ldsb + L_V + (vt >> 2) * 16384 + v_rd_base(lane) + (vt & 3) * 512;
;           s16x4 vl0, vh0, vl1, vh1, vl2, vh2, vl3, vh3;
;     ...
;           if (!lat) GLA_LOADV();
.LBB0_438:
.LBB0_439:
	v_mbcnt_lo_u32_b32 v64, -1, 0
	v_mbcnt_hi_u32_b32 v64, -1, v64
	s_andn2_b64 vcc, exec, s[34:35]
	v_add_u32_e32 v64, s72, v64
	s_nop 0
	v_and_b32_e32 v65, 63, v64
	v_lshlrev_b32_e32 v67, 4, v64
	v_lshlrev_b32_e32 v66, 3, v65
	v_and_b32_e32 v67, 0xc0, v67
	v_lshlrev_b32_e32 v68, 1, v64
	v_and_or_b32 v67, v66, 24, v67
	v_and_b32_e32 v68, 32, v68
	v_and_b32_e32 v66, 0x100, v66
	v_or3_b32 v154, v67, v68, v66
	v_cndmask_b32_e64 v66, 0, 1, s[34:35]
	v_cmp_ne_u32_e64 s[4:5], 1, v66
	v_add_u32_e32 v158, s48, v154
	s_cbranch_vccnz .LBB0_445
	ds_read_b64_tr_b16 v[136:137], v158 offset:0
	ds_read_b64_tr_b16 v[138:139], v158 offset:0x800
	ds_read_b64_tr_b16 v[140:141], v158 offset:0x1000
	ds_read_b64_tr_b16 v[142:143], v158 offset:0x1800
	ds_read_b64_tr_b16 v[144:145], v158 offset:0x2000
	ds_read_b64_tr_b16 v[146:147], v158 offset:0x2800
	ds_read_b64_tr_b16 v[148:149], v158 offset:0x3000
	ds_read_b64_tr_b16 v[150:151], v158 offset:0x3800
	s_and_b64 vcc, exec, s[4:5]
	s_mov_b64 s[4:5], -1
	s_cbranch_vccz .LBB0_446

; __device__ __forceinline__ unsigned pk2(float lo, float hi) { f32x2_t v = {lo, hi}; bf16x2_t b = __builtin_convertvector(v, bf16x2_t); return __builtin_bit_cast(unsigned, b); }
; __device__ __forceinline__ void scan_unit(const int unit, const Args& a, unsigned char* lds, const int mk_wid) {
;     ...
;             __syncthreads();
;     ...
;               f32x16 o0 = f32x16{}, o1 = f32x16{};
; #pragma unroll
;               for (int ct = 0; ct < 4; ++ct)
; #pragma unroll
;                 for (int kb = 0; kb < 2; ++kb) { const int cb = ct * 32 + kb * 16;
;                     v4u sw; sw.x = pk2(S[ct][8 * kb + 0], S[ct][8 * kb + 1]); sw.y = pk2(S[ct][8 * kb + 2], S[ct][8 * kb + 3]); sw.z = pk2(S[ct][8 * kb + 4], S[ct][8 * kb + 5]); sw.w = pk2(S[ct][8 * kb + 6], S[ct][8 * kb + 7]);
;                     const bf16x8 sb = __builtin_bit_cast(bf16x8, sw);
;                     { const u16* p0 = qe + r32 * QP + cb + 4 * hi; const v2u lo = *(const v2u*)p0, hh = *(const v2u*)(p0 + 8); v4u aw = {lo.x, lo.y, hh.x, hh.y};
;                       o0 = __builtin_amdgcn_mfma_f32_32x32x16_bf16(__builtin_bit_cast(bf16x8, aw), sb, o0, 0, 0, 0); }
;                     { const u16* p1 = qe + (32 + r32) * QP + cb + 4 * hi; const v2u lo = *(const v2u*)p1, hh = *(const v2u*)(p1 + 8); v4u aw = {lo.x, lo.y, hh.x, hh.y};
;                       o1 = __builtin_amdgcn_mfma_f32_32x32x16_bf16(__builtin_bit_cast(bf16x8, aw), sb, o1, 0, 0, 0); } }
;               GLA_LOADV();
;               asm volatile("s_waitcnt lgkmcnt(0)" ::: "memory"); GLA_SBAR();
;               { const u16* a0 = am + r32 * AP + hi * 8; const u16* a1 = am + (32 + r32) * AP + hi * 8;
;                 o0 = __builtin_amdgcn_mfma_f32_32x32x16_bf16(*(const bf16x8*)(a0), GLA_PK(vl0, vh0), o0, 0, 0, 0);
;                 o0 = __builtin_amdgcn_mfma_f32_32x32x16_bf16(*(const bf16x8*)(a0 + 16), GLA_PK(vl1, vh1), o0, 0, 0, 0);
;                 o1 = __builtin_amdgcn_mfma_f32_32x32x16_bf16(*(const bf16x8*)(a1), GLA_PK(vl0, vh0), o1, 0, 0, 0);
;                 o1 = __builtin_amdgcn_mfma_f32_32x32x16_bf16(*(const bf16x8*)(a1 + 16), GLA_PK(vl1, vh1), o1, 0, 0, 0);
;                 o1 = __builtin_amdgcn_mfma_f32_32x32x16_bf16(*(const bf16x8*)(a1 + 32), GLA_PK(vl2, vh2), o1, 0, 0, 0);
;                 o1 = __builtin_amdgcn_mfma_f32_32x32x16_bf16(*(const bf16x8*)(a1 + 48), GLA_PK(vl3, vh3), o1, 0, 0, 0); }
.LBB0_442:
	v_and_b32_e32 v168, 31, v64
	v_mul_u32_u24_e32 v64, 0x110, v168
	v_lshlrev_b32_e32 v65, 4, v157
	v_add3_u32 v144, 0, v64, v65
	ds_read_b128 v[170:173], v144
	ds_read_b128 v[174:177], v144 offset:32
	ds_read_b128 v[178:181], v144 offset:8704
	ds_read_b128 v[182:185], v144 offset:8736
	ds_read_b128 v[186:189], v144 offset:64
	ds_read_b128 v[190:193], v144 offset:8768
	ds_read_b128 v[194:197], v144 offset:96
	ds_read_b128 v[198:201], v144 offset:8800
	ds_read_b128 v[202:205], v144 offset:128
	ds_read_b128 v[206:209], v144 offset:8832
	ds_read_b128 v[210:213], v144 offset:160
	ds_read_b128 v[214:217], v144 offset:8864
	ds_read_b128 v[218:221], v144 offset:192
	ds_read_b128 v[222:225], v144 offset:8896
	ds_read_b128 v[226:229], v144 offset:224
	v_cvt_pk_bf16_f32 v80, v0, v1
	v_cvt_pk_bf16_f32 v81, v2, v3
	v_cvt_pk_bf16_f32 v82, v4, v5
	v_cvt_pk_bf16_f32 v83, v6, v7
	s_waitcnt lgkmcnt(14)
	s_nop 0
	v_mfma_f32_32x32x16_bf16 v[64:79], v[170:173], v[80:83], 0
	ds_read_b128 v[230:233], v144 offset:8928
	v_cvt_pk_bf16_f32 v140, v8, v9
	v_cvt_pk_bf16_f32 v141, v10, v11
	v_cvt_pk_bf16_f32 v142, v12, v13
	v_cvt_pk_bf16_f32 v143, v14, v15
	v_cvt_pk_bf16_f32 v160, v56, v57
	v_cvt_pk_bf16_f32 v161, v58, v59
	v_cvt_pk_bf16_f32 v162, v60, v61
	v_cvt_pk_bf16_f32 v163, v62, v63
	s_waitcnt lgkmcnt(14)
	s_nop 0
	v_mfma_f32_32x32x16_bf16 v[64:79], v[174:177], v[140:143], v[64:79]
	s_waitcnt lgkmcnt(13)
	v_mfma_f32_32x32x16_bf16 v[80:95], v[178:181], v[80:83], 0
	s_waitcnt lgkmcnt(12)
	v_mfma_f32_32x32x16_bf16 v[80:95], v[182:185], v[140:143], v[80:95]
	v_cvt_pk_bf16_f32 v140, v16, v17
	v_cvt_pk_bf16_f32 v141, v18, v19
	v_cvt_pk_bf16_f32 v142, v20, v21
	v_cvt_pk_bf16_f32 v143, v22, v23
	s_waitcnt lgkmcnt(11)
	s_nop 0
	v_mfma_f32_32x32x16_bf16 v[64:79], v[186:189], v[140:143], v[64:79]
	s_waitcnt lgkmcnt(10)
	v_mfma_f32_32x32x16_bf16 v[80:95], v[190:193], v[140:143], v[80:95]
	v_cvt_pk_bf16_f32 v140, v24, v25
	v_cvt_pk_bf16_f32 v141, v26, v27
	v_cvt_pk_bf16_f32 v142, v28, v29
	v_cvt_pk_bf16_f32 v143, v30, v31
	s_waitcnt lgkmcnt(9)
	s_nop 0
	v_mfma_f32_32x32x16_bf16 v[64:79], v[194:197], v[140:143], v[64:79]
	s_waitcnt lgkmcnt(8)
	v_mfma_f32_32x32x16_bf16 v[80:95], v[198:201], v[140:143], v[80:95]
	v_cvt_pk_bf16_f32 v140, v32, v33
	v_cvt_pk_bf16_f32 v141, v34, v35
	v_cvt_pk_bf16_f32 v142, v36, v37
	v_cvt_pk_bf16_f32 v143, v38, v39
	s_waitcnt lgkmcnt(7)
	s_nop 0
	v_mfma_f32_32x32x16_bf16 v[64:79], v[202:205], v[140:143], v[64:79]
	s_waitcnt lgkmcnt(6)
	v_mfma_f32_32x32x16_bf16 v[80:95], v[206:209], v[140:143], v[80:95]
	v_cvt_pk_bf16_f32 v140, v40, v41
	v_cvt_pk_bf16_f32 v141, v42, v43
	v_cvt_pk_bf16_f32 v142, v44, v45
	v_cvt_pk_bf16_f32 v143, v46, v47
	s_waitcnt lgkmcnt(5)
	s_nop 0
	v_mfma_f32_32x32x16_bf16 v[64:79], v[210:213], v[140:143], v[64:79]
	s_waitcnt lgkmcnt(4)
	v_mfma_f32_32x32x16_bf16 v[80:95], v[214:217], v[140:143], v[80:95]
	v_cvt_pk_bf16_f32 v140, v48, v49
	v_cvt_pk_bf16_f32 v141, v50, v51
	v_cvt_pk_bf16_f32 v142, v52, v53
	v_cvt_pk_bf16_f32 v143, v54, v55
	s_waitcnt lgkmcnt(3)
	s_nop 0
	v_mfma_f32_32x32x16_bf16 v[64:79], v[218:221], v[140:143], v[64:79]
	s_waitcnt lgkmcnt(2)
	v_mfma_f32_32x32x16_bf16 v[80:95], v[222:225], v[140:143], v[80:95]
	v_mul_u32_u24_e32 v236, 0x90, v168
	v_lshlrev_b32_e32 v237, 4, v157
	v_add3_u32 v236, s57, v236, v237
	s_waitcnt lgkmcnt(0)
	s_barrier
	ds_read_b128 v[170:173], v236
	ds_read_b128 v[174:177], v236 offset:32
	ds_read_b128 v[178:181], v236 offset:4608
	ds_read_b128 v[182:185], v236 offset:4640
	ds_read_b128 v[186:189], v236 offset:4672
	ds_read_b128 v[190:193], v236 offset:4704
	ds_read_b64_tr_b16 v[136:137], v158 offset:0
	s_waitcnt lgkmcnt(8)
	v_mfma_f32_32x32x16_bf16 v[64:79], v[226:229], v[160:163], v[64:79]
	ds_read_b64_tr_b16 v[138:139], v158 offset:0x800
	ds_read_b64_tr_b16 v[140:141], v158 offset:0x1000
	ds_read_b64_tr_b16 v[142:143], v158 offset:0x1800
	ds_read_b64_tr_b16 v[144:145], v158 offset:0x2000
	ds_read_b64_tr_b16 v[146:147], v158 offset:0x2800
	ds_read_b64_tr_b16 v[148:149], v158 offset:0x3000
	ds_read_b64_tr_b16 v[150:151], v158 offset:0x3800
	s_waitcnt lgkmcnt(0)
	v_mfma_f32_32x32x16_bf16 v[80:95], v[230:233], v[160:163], v[80:95]
	s_mov_b32 s34, s42
	v_mfma_f32_32x32x16_bf16 v[64:79], v[170:173], v[136:139], v[64:79]
	v_mfma_f32_32x32x16_bf16 v[64:79], v[174:177], v[140:143], v[64:79]
	v_mfma_f32_32x32x16_bf16 v[80:95], v[178:181], v[136:139], v[80:95]
	v_mfma_f32_32x32x16_bf16 v[80:95], v[182:185], v[140:143], v[80:95]
	v_mfma_f32_32x32x16_bf16 v[80:95], v[186:189], v[144:147], v[80:95]
	v_mfma_f32_32x32x16_bf16 v[80:95], v[190:193], v[148:151], v[80:95]
